# attention loop: LDS fragment addresses precomputed per unit (no per-group address adds), P fragments overlay their score registers
# baseline (speedup 1.0000x reference)
.LBB0_404:
	v_readfirstlane_b32 s13, v0
	s_nop 1
	v_cmp_eq_u32_e32 vcc, s13, v0
	s_and_saveexec_b64 vcc, vcc
	s_nop 0
	buffer_load_dwordx4 v205, s[28:31], s13 offen lds
	s_xor_b64 exec, exec, vcc
	s_cbranch_execnz .LBB0_404
	s_mov_b64 exec, s[10:11]
	s_mov_b32 m0, s90
	v_add_u32_e32 v175, v207, v201
	buffer_load_dwordx4 v206, s[36:39], s12 offen lds
	s_bitset1_b32 s12, 21
	s_mov_b32 m0, s91
	v_add_u32_e32 v217, v207, v202
	buffer_load_dwordx4 v206, s[36:39], s12 offen lds
	s_waitcnt vmcnt(4)
	s_barrier
	ds_read_b128 v[0:3], v175 offset:4096
	ds_read_b128 v[4:7], v175
	s_waitcnt vmcnt(15) lgkmcnt(0)
	v_mfma_f32_32x32x16_bf16 v[112:127], v[4:7], v[140:143], 0
	v_add_u32_e32 v218, v207, v203
	v_add_u32_e32 v219, v207, v204
	s_or_b32 s10, s85, 1
	s_mov_b32 s12, 0
	s_cmp_lt_u32 s1, 2
	v_mfma_f32_32x32x16_bf16 v[96:111], v[0:3], v[140:143], 0
	ds_read_b128 v[0:3], v217 offset:4096
	ds_read_b128 v[4:7], v217
	s_waitcnt vmcnt(14) lgkmcnt(0)
	v_mfma_f32_32x32x16_bf16 v[112:127], v[4:7], v[136:139], v[112:127]
	v_mfma_f32_32x32x16_bf16 v[96:111], v[0:3], v[136:139], v[96:111]
	ds_read_b128 v[0:3], v218 offset:4096
	ds_read_b128 v[4:7], v218
	s_waitcnt vmcnt(13) lgkmcnt(0)
	v_mfma_f32_32x32x16_bf16 v[112:127], v[4:7], v[132:135], v[112:127]
	v_mfma_f32_32x32x16_bf16 v[96:111], v[0:3], v[132:135], v[96:111]
	ds_read_b128 v[0:3], v219 offset:4096
	ds_read_b128 v[4:7], v219
	s_waitcnt vmcnt(12) lgkmcnt(0)
	v_mfma_f32_32x32x16_bf16 v[112:127], v[4:7], v[128:131], v[112:127]
	v_mfma_f32_32x32x16_bf16 v[96:111], v[0:3], v[128:131], v[96:111]
	s_mov_b32 s14, 0
	s_mov_b32 s15, s10
	s_mov_b32 s16, s85
	s_mov_b32 s38, s30
	s_mov_b32 s39, s31
	v_add_u32_e32 v240, v209, v201
	v_add_u32_e32 v244, v208, v201
	v_add_u32_e32 v248, v211, v201
	v_add_u32_e32 v241, v209, v202
	v_add_u32_e32 v245, v208, v202
	v_add_u32_e32 v249, v211, v202
	v_add_u32_e32 v242, v209, v203
	v_add_u32_e32 v246, v208, v203
	v_add_u32_e32 v250, v211, v203
	v_add_u32_e32 v243, v209, v204
	v_add_u32_e32 v247, v208, v204
	v_add_u32_e32 v251, v211, v204
	ds_read_b128 v[144:147], v175 offset:32768
	ds_read_b128 v[148:151], v175 offset:36864
	ds_read_b128 v[152:155], v217 offset:32768
	ds_read_b128 v[156:159], v217 offset:36864
	v_mov_b32_e32 v220, 0
	v_mov_b32_e32 v0, 0
	v_mov_b32_e32 v1, 0
	v_mov_b32_e32 v2, 0
	v_mov_b32_e32 v3, 0
	v_mov_b32_e32 v4, 0
	v_mov_b32_e32 v5, 0
	v_mov_b32_e32 v6, 0
	v_mov_b32_e32 v7, 0
	v_mov_b32_e32 v8, 0
	v_mov_b32_e32 v9, 0
	v_mov_b32_e32 v10, 0
	v_mov_b32_e32 v11, 0
	v_mov_b32_e32 v12, 0
	v_mov_b32_e32 v13, 0
	v_mov_b32_e32 v14, 0
	v_mov_b32_e32 v15, 0
	v_mov_b32_e32 v16, 0
	v_mov_b32_e32 v17, 0
	v_mov_b32_e32 v18, 0
	v_mov_b32_e32 v19, 0
	v_mov_b32_e32 v20, 0
	v_mov_b32_e32 v21, 0
	v_mov_b32_e32 v22, 0
	v_mov_b32_e32 v23, 0
	v_mov_b32_e32 v24, 0
	v_mov_b32_e32 v25, 0
	v_mov_b32_e32 v26, 0
	v_mov_b32_e32 v27, 0
	v_mov_b32_e32 v28, 0
	v_mov_b32_e32 v29, 0
	v_mov_b32_e32 v30, 0
	v_mov_b32_e32 v31, 0
	v_mov_b32_e32 v32, 0
	v_mov_b32_e32 v33, 0
	v_mov_b32_e32 v34, 0
	v_mov_b32_e32 v35, 0
	v_mov_b32_e32 v36, 0
	v_mov_b32_e32 v37, 0
	v_mov_b32_e32 v38, 0
	v_mov_b32_e32 v39, 0
	v_mov_b32_e32 v40, 0
	v_mov_b32_e32 v41, 0
	v_mov_b32_e32 v42, 0
	v_mov_b32_e32 v43, 0
	v_mov_b32_e32 v44, 0
	v_mov_b32_e32 v45, 0
	v_mov_b32_e32 v46, 0
	v_mov_b32_e32 v47, 0
	v_mov_b32_e32 v48, 0
	v_mov_b32_e32 v49, 0
	v_mov_b32_e32 v50, 0
	v_mov_b32_e32 v51, 0
	v_mov_b32_e32 v52, 0
	v_mov_b32_e32 v53, 0
	v_mov_b32_e32 v54, 0
	v_mov_b32_e32 v55, 0
	v_mov_b32_e32 v56, 0
	v_mov_b32_e32 v57, 0
	v_mov_b32_e32 v58, 0
	v_mov_b32_e32 v59, 0
	v_mov_b32_e32 v60, 0
	v_mov_b32_e32 v61, 0
	v_mov_b32_e32 v62, 0
	v_mov_b32_e32 v63, 0
	s_cmp_lt_u32 s16, 4
	s_cbranch_scc1 .Lat_rem_check
.Lat_main:
	s_add_i32 s17, s14, 3
	s_min_u32 s17, s17, s15
	s_mul_i32 s18, s17, 0x30000
	s_lshl_b32 s19, s17, 7
	s_or_b32 s98, s18, 0x80
	s_add_i32 s99, s19, 0x200000
	ds_read_b128 v[224:227], v218 offset:32768
	ds_read_b128 v[228:231], v218 offset:36864
	ds_read_b128 v[232:235], v219 offset:32768
	ds_read_b128 v[236:239], v219 offset:36864
	s_waitcnt lgkmcnt(4)
	v_mfma_f32_32x32x16_bf16 v[80:95], v[144:147], v[140:143], 0
	v_exp_f32_e32 v112, v112
	v_exp_f32_e32 v113, v113
	v_add_f32_e32 v220, v220, v112
	v_add_f32_e32 v220, v220, v113
	v_mfma_f32_32x32x16_bf16 v[64:79], v[148:151], v[140:143], 0
	v_exp_f32_e32 v114, v114
	v_exp_f32_e32 v115, v115
	v_add_f32_e32 v220, v220, v114
	v_add_f32_e32 v220, v220, v115
	v_mfma_f32_32x32x16_bf16 v[80:95], v[152:155], v[136:139], v[80:95]
	v_exp_f32_e32 v116, v116
	v_exp_f32_e32 v117, v117
	v_cvt_pk_bf16_f32 v112, v112, v113
	v_add_f32_e32 v220, v220, v116
	v_mfma_f32_32x32x16_bf16 v[64:79], v[156:159], v[136:139], v[64:79]
	v_exp_f32_e32 v118, v118
	v_exp_f32_e32 v119, v119
	v_cvt_pk_bf16_f32 v113, v114, v115
	v_add_f32_e32 v220, v220, v117
	ds_read_b128 v[144:147], v244 offset:16384
	ds_read_b128 v[148:151], v244 offset:20480
	ds_read_b128 v[152:155], v244 offset:24576
	ds_read_b128 v[156:159], v244 offset:28672
	s_waitcnt lgkmcnt(4)
	v_mfma_f32_32x32x16_bf16 v[80:95], v[224:227], v[132:135], v[80:95]
	v_cvt_pk_bf16_f32 v114, v116, v117
	v_cvt_pk_bf16_f32 v115, v118, v119
	v_exp_f32_e32 v120, v120
	v_exp_f32_e32 v121, v121
	v_mfma_f32_32x32x16_bf16 v[64:79], v[228:231], v[132:135], v[64:79]
	v_exp_f32_e32 v122, v122
	v_exp_f32_e32 v123, v123
	v_add_f32_e32 v220, v220, v120
	v_add_f32_e32 v220, v220, v121
	v_mfma_f32_32x32x16_bf16 v[80:95], v[232:235], v[128:131], v[80:95]
	v_exp_f32_e32 v124, v124
	v_exp_f32_e32 v125, v125
	v_add_f32_e32 v220, v220, v122
	v_add_f32_e32 v220, v220, v123
	v_mfma_f32_32x32x16_bf16 v[64:79], v[236:239], v[128:131], v[64:79]
	v_exp_f32_e32 v126, v126
	v_exp_f32_e32 v127, v127
	v_cvt_pk_bf16_f32 v120, v120, v121
	v_add_f32_e32 v220, v220, v118
	ds_read_b128 v[224:227], v245 offset:16384
	ds_read_b128 v[228:231], v245 offset:20480
	ds_read_b128 v[232:235], v245 offset:24576
	ds_read_b128 v[236:239], v245 offset:28672
	s_waitcnt lgkmcnt(4)
	v_mfma_f32_32x32x16_bf16 v[48:63], v[144:147], v[112:115], v[48:63]
	v_cvt_pk_bf16_f32 v121, v122, v123
	v_exp_f32_e32 v96, v96
	v_cvt_pk_bf16_f32 v122, v124, v125
	v_exp_f32_e32 v97, v97
	v_mfma_f32_32x32x16_bf16 v[32:47], v[148:151], v[112:115], v[32:47]
	v_cvt_pk_bf16_f32 v123, v126, v127
	v_exp_f32_e32 v98, v98
	v_exp_f32_e32 v99, v99
	v_add_f32_e32 v220, v220, v96
	v_mfma_f32_32x32x16_bf16 v[16:31], v[152:155], v[112:115], v[16:31]
	v_exp_f32_e32 v100, v100
	v_exp_f32_e32 v101, v101
	v_add_f32_e32 v220, v220, v97
	v_add_f32_e32 v220, v220, v98
	v_mfma_f32_32x32x16_bf16 v[0:15], v[156:159], v[112:115], v[0:15]
	v_exp_f32_e32 v102, v102
	v_exp_f32_e32 v103, v103
	v_add_f32_e32 v220, v220, v99
	v_cvt_pk_bf16_f32 v96, v96, v97
	ds_read_b128 v[144:147], v246 offset:16384
	ds_read_b128 v[148:151], v246 offset:20480
	ds_read_b128 v[152:155], v246 offset:24576
	ds_read_b128 v[156:159], v246 offset:28672
	s_waitcnt lgkmcnt(4)
	v_mfma_f32_32x32x16_bf16 v[48:63], v[224:227], v[120:123], v[48:63]
	v_cvt_pk_bf16_f32 v97, v98, v99
	v_exp_f32_e32 v104, v104
	v_cvt_pk_bf16_f32 v98, v100, v101
	v_exp_f32_e32 v105, v105
	v_mfma_f32_32x32x16_bf16 v[32:47], v[228:231], v[120:123], v[32:47]
	v_cvt_pk_bf16_f32 v99, v102, v103
	v_exp_f32_e32 v106, v106
	v_exp_f32_e32 v107, v107
	v_add_f32_e32 v220, v220, v104
	v_mfma_f32_32x32x16_bf16 v[16:31], v[232:235], v[120:123], v[16:31]
	v_exp_f32_e32 v108, v108
	v_exp_f32_e32 v109, v109
	v_add_f32_e32 v220, v220, v105
	v_add_f32_e32 v220, v220, v106
	v_mfma_f32_32x32x16_bf16 v[0:15], v[236:239], v[120:123], v[0:15]
	v_exp_f32_e32 v110, v110
	v_exp_f32_e32 v111, v111
	v_add_f32_e32 v220, v220, v107
	v_cvt_pk_bf16_f32 v104, v104, v105
	ds_read_b128 v[224:227], v247 offset:16384
	ds_read_b128 v[228:231], v247 offset:20480
	ds_read_b128 v[232:235], v247 offset:24576
	ds_read_b128 v[236:239], v247 offset:28672
	s_waitcnt lgkmcnt(4)
	s_mov_b32 m0, s92
	v_mfma_f32_32x32x16_bf16 v[48:63], v[144:147], v[96:99], v[48:63]
	buffer_load_dwordx4 v205, s[28:31], s18 offen lds
	v_cvt_pk_bf16_f32 v105, v106, v107
	v_add_f32_e32 v220, v220, v119
	s_mov_b32 m0, s93
	v_mfma_f32_32x32x16_bf16 v[32:47], v[148:151], v[96:99], v[32:47]
	buffer_load_dwordx4 v205, s[28:31], s98 offen lds
	v_cvt_pk_bf16_f32 v106, v108, v109
	v_cvt_pk_bf16_f32 v107, v110, v111
	s_mov_b32 m0, s94
	v_mfma_f32_32x32x16_bf16 v[16:31], v[152:155], v[96:99], v[16:31]
	buffer_load_dwordx4 v206, s[36:39], s19 offen lds
	v_add_f32_e32 v220, v220, v124
	v_add_f32_e32 v220, v220, v125
	s_mov_b32 m0, s95
	v_mfma_f32_32x32x16_bf16 v[0:15], v[156:159], v[96:99], v[0:15]
	buffer_load_dwordx4 v206, s[36:39], s99 offen lds
	v_add_f32_e32 v220, v220, v126
	v_add_f32_e32 v220, v220, v127
	s_waitcnt vmcnt(4) lgkmcnt(0)
	s_barrier
	ds_read_b128 v[144:147], v240
	ds_read_b128 v[148:151], v240 offset:4096
	ds_read_b128 v[152:155], v241
	ds_read_b128 v[156:159], v241 offset:4096
	v_mfma_f32_32x32x16_bf16 v[48:63], v[224:227], v[104:107], v[48:63]
	v_add_f32_e32 v220, v220, v100
	v_add_f32_e32 v220, v220, v101
	v_add_f32_e32 v220, v220, v102
	v_mfma_f32_32x32x16_bf16 v[32:47], v[228:231], v[104:107], v[32:47]
	v_add_f32_e32 v220, v220, v103
	v_add_f32_e32 v220, v220, v108
	v_add_f32_e32 v220, v220, v109
	v_mfma_f32_32x32x16_bf16 v[16:31], v[232:235], v[104:107], v[16:31]
	v_add_f32_e32 v220, v220, v110
	v_add_f32_e32 v220, v220, v111
	v_mfma_f32_32x32x16_bf16 v[0:15], v[236:239], v[104:107], v[0:15]
	s_add_i32 s17, s14, 4
	s_min_u32 s17, s17, s15
	s_mul_i32 s18, s17, 0x30000
	s_lshl_b32 s19, s17, 7
	s_or_b32 s98, s18, 0x80
	s_add_i32 s99, s19, 0x200000
	ds_read_b128 v[224:227], v242
	ds_read_b128 v[228:231], v242 offset:4096
	ds_read_b128 v[232:235], v243
	ds_read_b128 v[236:239], v243 offset:4096
	s_waitcnt lgkmcnt(4)
	v_mfma_f32_32x32x16_bf16 v[112:127], v[144:147], v[140:143], 0
	v_exp_f32_e32 v80, v80
	v_exp_f32_e32 v81, v81
	v_add_f32_e32 v220, v220, v80
	v_add_f32_e32 v220, v220, v81
	v_mfma_f32_32x32x16_bf16 v[96:111], v[148:151], v[140:143], 0
	v_exp_f32_e32 v82, v82
	v_exp_f32_e32 v83, v83
	v_add_f32_e32 v220, v220, v82
	v_add_f32_e32 v220, v220, v83
	v_mfma_f32_32x32x16_bf16 v[112:127], v[152:155], v[136:139], v[112:127]
	v_exp_f32_e32 v84, v84
	v_exp_f32_e32 v85, v85
	v_cvt_pk_bf16_f32 v80, v80, v81
	v_add_f32_e32 v220, v220, v84
	v_mfma_f32_32x32x16_bf16 v[96:111], v[156:159], v[136:139], v[96:111]
	v_exp_f32_e32 v86, v86
	v_exp_f32_e32 v87, v87
	v_cvt_pk_bf16_f32 v81, v82, v83
	v_add_f32_e32 v220, v220, v85
	ds_read_b128 v[144:147], v244 offset:49152
	ds_read_b128 v[148:151], v244 offset:53248
	ds_read_b128 v[152:155], v244 offset:57344
	ds_read_b128 v[156:159], v244 offset:61440
	s_waitcnt lgkmcnt(4)
	v_mfma_f32_32x32x16_bf16 v[112:127], v[224:227], v[132:135], v[112:127]
	v_cvt_pk_bf16_f32 v82, v84, v85
	v_cvt_pk_bf16_f32 v83, v86, v87
	v_exp_f32_e32 v88, v88
	v_exp_f32_e32 v89, v89
	v_mfma_f32_32x32x16_bf16 v[96:111], v[228:231], v[132:135], v[96:111]
	v_exp_f32_e32 v90, v90
	v_exp_f32_e32 v91, v91
	v_add_f32_e32 v220, v220, v88
	v_add_f32_e32 v220, v220, v89
	v_mfma_f32_32x32x16_bf16 v[112:127], v[232:235], v[128:131], v[112:127]
	v_exp_f32_e32 v92, v92
	v_exp_f32_e32 v93, v93
	v_add_f32_e32 v220, v220, v90
	v_add_f32_e32 v220, v220, v91
	v_mfma_f32_32x32x16_bf16 v[96:111], v[236:239], v[128:131], v[96:111]
	v_exp_f32_e32 v94, v94
	v_exp_f32_e32 v95, v95
	v_cvt_pk_bf16_f32 v88, v88, v89
	v_add_f32_e32 v220, v220, v86
	ds_read_b128 v[224:227], v245 offset:49152
	ds_read_b128 v[228:231], v245 offset:53248
	ds_read_b128 v[232:235], v245 offset:57344
	ds_read_b128 v[236:239], v245 offset:61440
	s_waitcnt lgkmcnt(4)
	v_mfma_f32_32x32x16_bf16 v[48:63], v[144:147], v[80:83], v[48:63]
	v_cvt_pk_bf16_f32 v89, v90, v91
	v_exp_f32_e32 v64, v64
	v_cvt_pk_bf16_f32 v90, v92, v93
	v_exp_f32_e32 v65, v65
	v_mfma_f32_32x32x16_bf16 v[32:47], v[148:151], v[80:83], v[32:47]
	v_cvt_pk_bf16_f32 v91, v94, v95
	v_exp_f32_e32 v66, v66
	v_exp_f32_e32 v67, v67
	v_add_f32_e32 v220, v220, v64
	v_mfma_f32_32x32x16_bf16 v[16:31], v[152:155], v[80:83], v[16:31]
	v_exp_f32_e32 v68, v68
	v_exp_f32_e32 v69, v69
	v_add_f32_e32 v220, v220, v65
	v_add_f32_e32 v220, v220, v66
	v_mfma_f32_32x32x16_bf16 v[0:15], v[156:159], v[80:83], v[0:15]
	v_exp_f32_e32 v70, v70
	v_exp_f32_e32 v71, v71
	v_add_f32_e32 v220, v220, v67
	v_cvt_pk_bf16_f32 v64, v64, v65
	ds_read_b128 v[144:147], v246 offset:49152
	ds_read_b128 v[148:151], v246 offset:53248
	ds_read_b128 v[152:155], v246 offset:57344
	ds_read_b128 v[156:159], v246 offset:61440
	s_waitcnt lgkmcnt(4)
	v_mfma_f32_32x32x16_bf16 v[48:63], v[224:227], v[88:91], v[48:63]
	v_cvt_pk_bf16_f32 v65, v66, v67
	v_exp_f32_e32 v72, v72
	v_cvt_pk_bf16_f32 v66, v68, v69
	v_exp_f32_e32 v73, v73
	v_mfma_f32_32x32x16_bf16 v[32:47], v[228:231], v[88:91], v[32:47]
	v_cvt_pk_bf16_f32 v67, v70, v71
	v_exp_f32_e32 v74, v74
	v_exp_f32_e32 v75, v75
	v_add_f32_e32 v220, v220, v72
	v_mfma_f32_32x32x16_bf16 v[16:31], v[232:235], v[88:91], v[16:31]
	v_exp_f32_e32 v76, v76
	v_exp_f32_e32 v77, v77
	v_add_f32_e32 v220, v220, v73
	v_add_f32_e32 v220, v220, v74
	v_mfma_f32_32x32x16_bf16 v[0:15], v[236:239], v[88:91], v[0:15]
	v_exp_f32_e32 v78, v78
	v_exp_f32_e32 v79, v79
	v_add_f32_e32 v220, v220, v75
	v_cvt_pk_bf16_f32 v72, v72, v73
	ds_read_b128 v[224:227], v247 offset:49152
	ds_read_b128 v[228:231], v247 offset:53248
	ds_read_b128 v[232:235], v247 offset:57344
	ds_read_b128 v[236:239], v247 offset:61440
	s_waitcnt lgkmcnt(4)
	s_mov_b32 m0, s72
	v_mfma_f32_32x32x16_bf16 v[48:63], v[144:147], v[64:67], v[48:63]
	buffer_load_dwordx4 v205, s[28:31], s18 offen lds
	v_cvt_pk_bf16_f32 v73, v74, v75
	v_add_f32_e32 v220, v220, v87
	s_mov_b32 m0, s73
	v_mfma_f32_32x32x16_bf16 v[32:47], v[148:151], v[64:67], v[32:47]
	buffer_load_dwordx4 v205, s[28:31], s98 offen lds
	v_cvt_pk_bf16_f32 v74, v76, v77
	v_cvt_pk_bf16_f32 v75, v78, v79
	s_mov_b32 m0, s6
	v_mfma_f32_32x32x16_bf16 v[16:31], v[152:155], v[64:67], v[16:31]
	buffer_load_dwordx4 v206, s[36:39], s19 offen lds
	v_add_f32_e32 v220, v220, v92
	v_add_f32_e32 v220, v220, v93
	s_mov_b32 m0, s7
	v_mfma_f32_32x32x16_bf16 v[0:15], v[156:159], v[64:67], v[0:15]
	buffer_load_dwordx4 v206, s[36:39], s99 offen lds
	v_add_f32_e32 v220, v220, v94
	v_add_f32_e32 v220, v220, v95
	s_waitcnt vmcnt(4) lgkmcnt(0)
	s_barrier
	ds_read_b128 v[144:147], v240 offset:32768
	ds_read_b128 v[148:151], v240 offset:36864
	ds_read_b128 v[152:155], v241 offset:32768
	ds_read_b128 v[156:159], v241 offset:36864
	v_mfma_f32_32x32x16_bf16 v[48:63], v[224:227], v[72:75], v[48:63]
	v_add_f32_e32 v220, v220, v68
	v_add_f32_e32 v220, v220, v69
	v_add_f32_e32 v220, v220, v70
	v_mfma_f32_32x32x16_bf16 v[32:47], v[228:231], v[72:75], v[32:47]
	v_add_f32_e32 v220, v220, v71
	v_add_f32_e32 v220, v220, v76
	v_add_f32_e32 v220, v220, v77
	v_mfma_f32_32x32x16_bf16 v[16:31], v[232:235], v[72:75], v[16:31]
	v_add_f32_e32 v220, v220, v78
	v_add_f32_e32 v220, v220, v79
	v_mfma_f32_32x32x16_bf16 v[0:15], v[236:239], v[72:75], v[0:15]
	s_add_i32 s17, s14, 5
	s_min_u32 s17, s17, s15
	s_mul_i32 s18, s17, 0x30000
	s_lshl_b32 s19, s17, 7
	s_or_b32 s98, s18, 0x80
	s_add_i32 s99, s19, 0x200000
	ds_read_b128 v[224:227], v242 offset:32768
	ds_read_b128 v[228:231], v242 offset:36864
	ds_read_b128 v[232:235], v243 offset:32768
	ds_read_b128 v[236:239], v243 offset:36864
	s_waitcnt lgkmcnt(4)
	v_mfma_f32_32x32x16_bf16 v[80:95], v[144:147], v[140:143], 0
	v_exp_f32_e32 v112, v112
	v_exp_f32_e32 v113, v113
	v_add_f32_e32 v220, v220, v112
	v_add_f32_e32 v220, v220, v113
	v_mfma_f32_32x32x16_bf16 v[64:79], v[148:151], v[140:143], 0
	v_exp_f32_e32 v114, v114
	v_exp_f32_e32 v115, v115
	v_add_f32_e32 v220, v220, v114
	v_add_f32_e32 v220, v220, v115
	v_mfma_f32_32x32x16_bf16 v[80:95], v[152:155], v[136:139], v[80:95]
	v_exp_f32_e32 v116, v116
	v_exp_f32_e32 v117, v117
	v_cvt_pk_bf16_f32 v112, v112, v113
	v_add_f32_e32 v220, v220, v116
	v_mfma_f32_32x32x16_bf16 v[64:79], v[156:159], v[136:139], v[64:79]
	v_exp_f32_e32 v118, v118
	v_exp_f32_e32 v119, v119
	v_cvt_pk_bf16_f32 v113, v114, v115
	v_add_f32_e32 v220, v220, v117
	ds_read_b128 v[144:147], v248
	ds_read_b128 v[148:151], v248 offset:4096
	ds_read_b128 v[152:155], v248 offset:8192
	ds_read_b128 v[156:159], v248 offset:12288
	s_waitcnt lgkmcnt(4)
	v_mfma_f32_32x32x16_bf16 v[80:95], v[224:227], v[132:135], v[80:95]
	v_cvt_pk_bf16_f32 v114, v116, v117
	v_cvt_pk_bf16_f32 v115, v118, v119
	v_exp_f32_e32 v120, v120
	v_exp_f32_e32 v121, v121
	v_mfma_f32_32x32x16_bf16 v[64:79], v[228:231], v[132:135], v[64:79]
	v_exp_f32_e32 v122, v122
	v_exp_f32_e32 v123, v123
	v_add_f32_e32 v220, v220, v120
	v_add_f32_e32 v220, v220, v121
	v_mfma_f32_32x32x16_bf16 v[80:95], v[232:235], v[128:131], v[80:95]
	v_exp_f32_e32 v124, v124
	v_exp_f32_e32 v125, v125
	v_add_f32_e32 v220, v220, v122
	v_add_f32_e32 v220, v220, v123
	v_mfma_f32_32x32x16_bf16 v[64:79], v[236:239], v[128:131], v[64:79]
	v_exp_f32_e32 v126, v126
	v_exp_f32_e32 v127, v127
	v_cvt_pk_bf16_f32 v120, v120, v121
	v_add_f32_e32 v220, v220, v118
	ds_read_b128 v[224:227], v249
	ds_read_b128 v[228:231], v249 offset:4096
	ds_read_b128 v[232:235], v249 offset:8192
	ds_read_b128 v[236:239], v249 offset:12288
	s_waitcnt lgkmcnt(4)
	v_mfma_f32_32x32x16_bf16 v[48:63], v[144:147], v[112:115], v[48:63]
	v_cvt_pk_bf16_f32 v121, v122, v123
	v_exp_f32_e32 v96, v96
	v_cvt_pk_bf16_f32 v122, v124, v125
	v_exp_f32_e32 v97, v97
	v_mfma_f32_32x32x16_bf16 v[32:47], v[148:151], v[112:115], v[32:47]
	v_cvt_pk_bf16_f32 v123, v126, v127
	v_exp_f32_e32 v98, v98
	v_exp_f32_e32 v99, v99
	v_add_f32_e32 v220, v220, v96
	v_mfma_f32_32x32x16_bf16 v[16:31], v[152:155], v[112:115], v[16:31]
	v_exp_f32_e32 v100, v100
	v_exp_f32_e32 v101, v101
	v_add_f32_e32 v220, v220, v97
	v_add_f32_e32 v220, v220, v98
	v_mfma_f32_32x32x16_bf16 v[0:15], v[156:159], v[112:115], v[0:15]
	v_exp_f32_e32 v102, v102
	v_exp_f32_e32 v103, v103
	v_add_f32_e32 v220, v220, v99
	v_cvt_pk_bf16_f32 v96, v96, v97
	ds_read_b128 v[144:147], v250
	ds_read_b128 v[148:151], v250 offset:4096
	ds_read_b128 v[152:155], v250 offset:8192
	ds_read_b128 v[156:159], v250 offset:12288
	s_waitcnt lgkmcnt(4)
	v_mfma_f32_32x32x16_bf16 v[48:63], v[224:227], v[120:123], v[48:63]
	v_cvt_pk_bf16_f32 v97, v98, v99
	v_exp_f32_e32 v104, v104
	v_cvt_pk_bf16_f32 v98, v100, v101
	v_exp_f32_e32 v105, v105
	v_mfma_f32_32x32x16_bf16 v[32:47], v[228:231], v[120:123], v[32:47]
	v_cvt_pk_bf16_f32 v99, v102, v103
	v_exp_f32_e32 v106, v106
	v_exp_f32_e32 v107, v107
	v_add_f32_e32 v220, v220, v104
	v_mfma_f32_32x32x16_bf16 v[16:31], v[232:235], v[120:123], v[16:31]
	v_exp_f32_e32 v108, v108
	v_exp_f32_e32 v109, v109
	v_add_f32_e32 v220, v220, v105
	v_add_f32_e32 v220, v220, v106
	v_mfma_f32_32x32x16_bf16 v[0:15], v[236:239], v[120:123], v[0:15]
	v_exp_f32_e32 v110, v110
	v_exp_f32_e32 v111, v111
	v_add_f32_e32 v220, v220, v107
	v_cvt_pk_bf16_f32 v104, v104, v105
	ds_read_b128 v[224:227], v251
	ds_read_b128 v[228:231], v251 offset:4096
	ds_read_b128 v[232:235], v251 offset:8192
	ds_read_b128 v[236:239], v251 offset:12288
	s_waitcnt lgkmcnt(4)
	s_mov_b32 m0, s8
	v_mfma_f32_32x32x16_bf16 v[48:63], v[144:147], v[96:99], v[48:63]
	buffer_load_dwordx4 v205, s[28:31], s18 offen lds
	v_cvt_pk_bf16_f32 v105, v106, v107
	v_add_f32_e32 v220, v220, v119
	s_mov_b32 m0, s9
	v_mfma_f32_32x32x16_bf16 v[32:47], v[148:151], v[96:99], v[32:47]
	buffer_load_dwordx4 v205, s[28:31], s98 offen lds
	v_cvt_pk_bf16_f32 v106, v108, v109
	v_cvt_pk_bf16_f32 v107, v110, v111
	s_mov_b32 m0, s58
	v_mfma_f32_32x32x16_bf16 v[16:31], v[152:155], v[96:99], v[16:31]
	buffer_load_dwordx4 v206, s[36:39], s19 offen lds
	v_add_f32_e32 v220, v220, v124
	v_add_f32_e32 v220, v220, v125
	s_mov_b32 m0, s79
	v_mfma_f32_32x32x16_bf16 v[0:15], v[156:159], v[96:99], v[0:15]
	buffer_load_dwordx4 v206, s[36:39], s99 offen lds
	v_add_f32_e32 v220, v220, v126
	v_add_f32_e32 v220, v220, v127
	s_waitcnt vmcnt(4) lgkmcnt(0)
	s_barrier
	ds_read_b128 v[144:147], v175
	ds_read_b128 v[148:151], v175 offset:4096
	ds_read_b128 v[152:155], v217
	ds_read_b128 v[156:159], v217 offset:4096
	v_mfma_f32_32x32x16_bf16 v[48:63], v[224:227], v[104:107], v[48:63]
	v_add_f32_e32 v220, v220, v100
	v_add_f32_e32 v220, v220, v101
	v_add_f32_e32 v220, v220, v102
	v_mfma_f32_32x32x16_bf16 v[32:47], v[228:231], v[104:107], v[32:47]
	v_add_f32_e32 v220, v220, v103
	v_add_f32_e32 v220, v220, v108
	v_add_f32_e32 v220, v220, v109
	v_mfma_f32_32x32x16_bf16 v[16:31], v[232:235], v[104:107], v[16:31]
	v_add_f32_e32 v220, v220, v110
	v_add_f32_e32 v220, v220, v111
	v_mfma_f32_32x32x16_bf16 v[0:15], v[236:239], v[104:107], v[0:15]
	s_add_i32 s17, s14, 6
	s_min_u32 s17, s17, s15
	s_mul_i32 s18, s17, 0x30000
	s_lshl_b32 s19, s17, 7
	s_or_b32 s98, s18, 0x80
	s_add_i32 s99, s19, 0x200000
	ds_read_b128 v[224:227], v218
	ds_read_b128 v[228:231], v218 offset:4096
	ds_read_b128 v[232:235], v219
	ds_read_b128 v[236:239], v219 offset:4096
	s_waitcnt lgkmcnt(4)
	v_mfma_f32_32x32x16_bf16 v[112:127], v[144:147], v[140:143], 0
	v_exp_f32_e32 v80, v80
	v_exp_f32_e32 v81, v81
	v_add_f32_e32 v220, v220, v80
	v_add_f32_e32 v220, v220, v81
	v_mfma_f32_32x32x16_bf16 v[96:111], v[148:151], v[140:143], 0
	v_exp_f32_e32 v82, v82
	v_exp_f32_e32 v83, v83
	v_add_f32_e32 v220, v220, v82
	v_add_f32_e32 v220, v220, v83
	v_mfma_f32_32x32x16_bf16 v[112:127], v[152:155], v[136:139], v[112:127]
	v_exp_f32_e32 v84, v84
	v_exp_f32_e32 v85, v85
	v_cvt_pk_bf16_f32 v80, v80, v81
	v_add_f32_e32 v220, v220, v84
	v_mfma_f32_32x32x16_bf16 v[96:111], v[156:159], v[136:139], v[96:111]
	v_exp_f32_e32 v86, v86
	v_exp_f32_e32 v87, v87
	v_cvt_pk_bf16_f32 v81, v82, v83
	v_add_f32_e32 v220, v220, v85
	ds_read_b128 v[144:147], v248 offset:32768
	ds_read_b128 v[148:151], v248 offset:36864
	ds_read_b128 v[152:155], v248 offset:40960
	ds_read_b128 v[156:159], v248 offset:45056
	s_waitcnt lgkmcnt(4)
	v_mfma_f32_32x32x16_bf16 v[112:127], v[224:227], v[132:135], v[112:127]
	v_cvt_pk_bf16_f32 v82, v84, v85
	v_cvt_pk_bf16_f32 v83, v86, v87
	v_exp_f32_e32 v88, v88
	v_exp_f32_e32 v89, v89
	v_mfma_f32_32x32x16_bf16 v[96:111], v[228:231], v[132:135], v[96:111]
	v_exp_f32_e32 v90, v90
	v_exp_f32_e32 v91, v91
	v_add_f32_e32 v220, v220, v88
	v_add_f32_e32 v220, v220, v89
	v_mfma_f32_32x32x16_bf16 v[112:127], v[232:235], v[128:131], v[112:127]
	v_exp_f32_e32 v92, v92
	v_exp_f32_e32 v93, v93
	v_add_f32_e32 v220, v220, v90
	v_add_f32_e32 v220, v220, v91
	v_mfma_f32_32x32x16_bf16 v[96:111], v[236:239], v[128:131], v[96:111]
	v_exp_f32_e32 v94, v94
	v_exp_f32_e32 v95, v95
	v_cvt_pk_bf16_f32 v88, v88, v89
	v_add_f32_e32 v220, v220, v86
	ds_read_b128 v[224:227], v249 offset:32768
	ds_read_b128 v[228:231], v249 offset:36864
	ds_read_b128 v[232:235], v249 offset:40960
	ds_read_b128 v[236:239], v249 offset:45056
	s_waitcnt lgkmcnt(4)
	v_mfma_f32_32x32x16_bf16 v[48:63], v[144:147], v[80:83], v[48:63]
	v_cvt_pk_bf16_f32 v89, v90, v91
	v_exp_f32_e32 v64, v64
	v_cvt_pk_bf16_f32 v90, v92, v93
	v_exp_f32_e32 v65, v65
	v_mfma_f32_32x32x16_bf16 v[32:47], v[148:151], v[80:83], v[32:47]
	v_cvt_pk_bf16_f32 v91, v94, v95
	v_exp_f32_e32 v66, v66
	v_exp_f32_e32 v67, v67
	v_add_f32_e32 v220, v220, v64
	v_mfma_f32_32x32x16_bf16 v[16:31], v[152:155], v[80:83], v[16:31]
	v_exp_f32_e32 v68, v68
	v_exp_f32_e32 v69, v69
	v_add_f32_e32 v220, v220, v65
	v_add_f32_e32 v220, v220, v66
	v_mfma_f32_32x32x16_bf16 v[0:15], v[156:159], v[80:83], v[0:15]
	v_exp_f32_e32 v70, v70
	v_exp_f32_e32 v71, v71
	v_add_f32_e32 v220, v220, v67
	v_cvt_pk_bf16_f32 v64, v64, v65
	ds_read_b128 v[144:147], v250 offset:32768
	ds_read_b128 v[148:151], v250 offset:36864
	ds_read_b128 v[152:155], v250 offset:40960
	ds_read_b128 v[156:159], v250 offset:45056
	s_waitcnt lgkmcnt(4)
	v_mfma_f32_32x32x16_bf16 v[48:63], v[224:227], v[88:91], v[48:63]
	v_cvt_pk_bf16_f32 v65, v66, v67
	v_exp_f32_e32 v72, v72
	v_cvt_pk_bf16_f32 v66, v68, v69
	v_exp_f32_e32 v73, v73
	v_mfma_f32_32x32x16_bf16 v[32:47], v[228:231], v[88:91], v[32:47]
	v_cvt_pk_bf16_f32 v67, v70, v71
	v_exp_f32_e32 v74, v74
	v_exp_f32_e32 v75, v75
	v_add_f32_e32 v220, v220, v72
	v_mfma_f32_32x32x16_bf16 v[16:31], v[232:235], v[88:91], v[16:31]
	v_exp_f32_e32 v76, v76
	v_exp_f32_e32 v77, v77
	v_add_f32_e32 v220, v220, v73
	v_add_f32_e32 v220, v220, v74
	v_mfma_f32_32x32x16_bf16 v[0:15], v[236:239], v[88:91], v[0:15]
	v_exp_f32_e32 v78, v78
	v_exp_f32_e32 v79, v79
	v_add_f32_e32 v220, v220, v75
	v_cvt_pk_bf16_f32 v72, v72, v73
	ds_read_b128 v[224:227], v251 offset:32768
	ds_read_b128 v[228:231], v251 offset:36864
	ds_read_b128 v[232:235], v251 offset:40960
	ds_read_b128 v[236:239], v251 offset:45056
	s_waitcnt lgkmcnt(4)
	s_mov_b32 m0, s52
	v_mfma_f32_32x32x16_bf16 v[48:63], v[144:147], v[64:67], v[48:63]
	buffer_load_dwordx4 v205, s[28:31], s18 offen lds
	v_cvt_pk_bf16_f32 v73, v74, v75
	v_add_f32_e32 v220, v220, v87
	s_mov_b32 m0, s53
	v_mfma_f32_32x32x16_bf16 v[32:47], v[148:151], v[64:67], v[32:47]
	buffer_load_dwordx4 v205, s[28:31], s98 offen lds
	v_cvt_pk_bf16_f32 v74, v76, v77
	v_cvt_pk_bf16_f32 v75, v78, v79
	s_mov_b32 m0, s90
	v_mfma_f32_32x32x16_bf16 v[16:31], v[152:155], v[64:67], v[16:31]
	buffer_load_dwordx4 v206, s[36:39], s19 offen lds
	v_add_f32_e32 v220, v220, v92
	v_add_f32_e32 v220, v220, v93
	s_mov_b32 m0, s91
	v_mfma_f32_32x32x16_bf16 v[0:15], v[156:159], v[64:67], v[0:15]
	buffer_load_dwordx4 v206, s[36:39], s99 offen lds
	v_add_f32_e32 v220, v220, v94
	v_add_f32_e32 v220, v220, v95
	s_waitcnt vmcnt(4) lgkmcnt(0)
	s_barrier
	ds_read_b128 v[144:147], v175 offset:32768
	ds_read_b128 v[148:151], v175 offset:36864
	ds_read_b128 v[152:155], v217 offset:32768
	ds_read_b128 v[156:159], v217 offset:36864
	v_mfma_f32_32x32x16_bf16 v[48:63], v[224:227], v[72:75], v[48:63]
	v_add_f32_e32 v220, v220, v68
	v_add_f32_e32 v220, v220, v69
	v_add_f32_e32 v220, v220, v70
	v_mfma_f32_32x32x16_bf16 v[32:47], v[228:231], v[72:75], v[32:47]
	v_add_f32_e32 v220, v220, v71
	v_add_f32_e32 v220, v220, v76
	v_add_f32_e32 v220, v220, v77
	v_mfma_f32_32x32x16_bf16 v[16:31], v[232:235], v[72:75], v[16:31]
	v_add_f32_e32 v220, v220, v78
	v_add_f32_e32 v220, v220, v79
	v_mfma_f32_32x32x16_bf16 v[0:15], v[236:239], v[72:75], v[0:15]
	s_add_i32 s14, s14, 4
	s_add_i32 s17, s14, 4
	s_cmp_le_u32 s17, s16
	s_cbranch_scc1 .Lat_main
.Lat_rem_check:
	s_cmp_ge_u32 s14, s16
	s_cbranch_scc1 .Lat_exit
	s_add_i32 s17, s14, 3
	s_min_u32 s17, s17, s15
	s_mul_i32 s18, s17, 0x30000
	s_lshl_b32 s19, s17, 7
	s_or_b32 s98, s18, 0x80
	s_add_i32 s99, s19, 0x200000
	ds_read_b128 v[224:227], v218 offset:32768
	ds_read_b128 v[228:231], v218 offset:36864
	ds_read_b128 v[232:235], v219 offset:32768
	ds_read_b128 v[236:239], v219 offset:36864
	s_waitcnt lgkmcnt(4)
	v_mfma_f32_32x32x16_bf16 v[80:95], v[144:147], v[140:143], 0
	v_exp_f32_e32 v112, v112
	v_exp_f32_e32 v113, v113
	v_add_f32_e32 v220, v220, v112
	v_add_f32_e32 v220, v220, v113
	v_mfma_f32_32x32x16_bf16 v[64:79], v[148:151], v[140:143], 0
	v_exp_f32_e32 v114, v114
	v_exp_f32_e32 v115, v115
	v_add_f32_e32 v220, v220, v114
	v_add_f32_e32 v220, v220, v115
	v_mfma_f32_32x32x16_bf16 v[80:95], v[152:155], v[136:139], v[80:95]
	v_exp_f32_e32 v116, v116
	v_exp_f32_e32 v117, v117
	v_cvt_pk_bf16_f32 v112, v112, v113
	v_add_f32_e32 v220, v220, v116
	v_mfma_f32_32x32x16_bf16 v[64:79], v[156:159], v[136:139], v[64:79]
	v_exp_f32_e32 v118, v118
	v_exp_f32_e32 v119, v119
	v_cvt_pk_bf16_f32 v113, v114, v115
	v_add_f32_e32 v220, v220, v117
	ds_read_b128 v[144:147], v244 offset:16384
	ds_read_b128 v[148:151], v244 offset:20480
	ds_read_b128 v[152:155], v244 offset:24576
	ds_read_b128 v[156:159], v244 offset:28672
	s_waitcnt lgkmcnt(4)
	v_mfma_f32_32x32x16_bf16 v[80:95], v[224:227], v[132:135], v[80:95]
	v_cvt_pk_bf16_f32 v114, v116, v117
	v_cvt_pk_bf16_f32 v115, v118, v119
	v_exp_f32_e32 v120, v120
	v_exp_f32_e32 v121, v121
	v_mfma_f32_32x32x16_bf16 v[64:79], v[228:231], v[132:135], v[64:79]
	v_exp_f32_e32 v122, v122
	v_exp_f32_e32 v123, v123
	v_add_f32_e32 v220, v220, v120
	v_add_f32_e32 v220, v220, v121
	v_mfma_f32_32x32x16_bf16 v[80:95], v[232:235], v[128:131], v[80:95]
	v_exp_f32_e32 v124, v124
	v_exp_f32_e32 v125, v125
	v_add_f32_e32 v220, v220, v122
	v_add_f32_e32 v220, v220, v123
	v_mfma_f32_32x32x16_bf16 v[64:79], v[236:239], v[128:131], v[64:79]
	v_exp_f32_e32 v126, v126
	v_exp_f32_e32 v127, v127
	v_cvt_pk_bf16_f32 v120, v120, v121
	v_add_f32_e32 v220, v220, v118
	ds_read_b128 v[224:227], v245 offset:16384
	ds_read_b128 v[228:231], v245 offset:20480
	ds_read_b128 v[232:235], v245 offset:24576
	ds_read_b128 v[236:239], v245 offset:28672
	s_waitcnt lgkmcnt(4)
	v_mfma_f32_32x32x16_bf16 v[48:63], v[144:147], v[112:115], v[48:63]
	v_cvt_pk_bf16_f32 v121, v122, v123
	v_exp_f32_e32 v96, v96
	v_cvt_pk_bf16_f32 v122, v124, v125
	v_exp_f32_e32 v97, v97
	v_mfma_f32_32x32x16_bf16 v[32:47], v[148:151], v[112:115], v[32:47]
	v_cvt_pk_bf16_f32 v123, v126, v127
	v_exp_f32_e32 v98, v98
	v_exp_f32_e32 v99, v99
	v_add_f32_e32 v220, v220, v96
	v_mfma_f32_32x32x16_bf16 v[16:31], v[152:155], v[112:115], v[16:31]
	v_exp_f32_e32 v100, v100
	v_exp_f32_e32 v101, v101
	v_add_f32_e32 v220, v220, v97
	v_add_f32_e32 v220, v220, v98
	v_mfma_f32_32x32x16_bf16 v[0:15], v[156:159], v[112:115], v[0:15]
	v_exp_f32_e32 v102, v102
	v_exp_f32_e32 v103, v103
	v_add_f32_e32 v220, v220, v99
	v_cvt_pk_bf16_f32 v96, v96, v97
	ds_read_b128 v[144:147], v246 offset:16384
	ds_read_b128 v[148:151], v246 offset:20480
	ds_read_b128 v[152:155], v246 offset:24576
	ds_read_b128 v[156:159], v246 offset:28672
	s_waitcnt lgkmcnt(4)
	v_mfma_f32_32x32x16_bf16 v[48:63], v[224:227], v[120:123], v[48:63]
	v_cvt_pk_bf16_f32 v97, v98, v99
	v_exp_f32_e32 v104, v104
	v_cvt_pk_bf16_f32 v98, v100, v101
	v_exp_f32_e32 v105, v105
	v_mfma_f32_32x32x16_bf16 v[32:47], v[228:231], v[120:123], v[32:47]
	v_cvt_pk_bf16_f32 v99, v102, v103
	v_exp_f32_e32 v106, v106
	v_exp_f32_e32 v107, v107
	v_add_f32_e32 v220, v220, v104
	v_mfma_f32_32x32x16_bf16 v[16:31], v[232:235], v[120:123], v[16:31]
	v_exp_f32_e32 v108, v108
	v_exp_f32_e32 v109, v109
	v_add_f32_e32 v220, v220, v105
	v_add_f32_e32 v220, v220, v106
	v_mfma_f32_32x32x16_bf16 v[0:15], v[236:239], v[120:123], v[0:15]
	v_exp_f32_e32 v110, v110
	v_exp_f32_e32 v111, v111
	v_add_f32_e32 v220, v220, v107
	v_cvt_pk_bf16_f32 v104, v104, v105
	ds_read_b128 v[224:227], v247 offset:16384
	ds_read_b128 v[228:231], v247 offset:20480
	ds_read_b128 v[232:235], v247 offset:24576
	ds_read_b128 v[236:239], v247 offset:28672
	s_waitcnt lgkmcnt(4)
	s_mov_b32 m0, s92
	v_mfma_f32_32x32x16_bf16 v[48:63], v[144:147], v[96:99], v[48:63]
	buffer_load_dwordx4 v205, s[28:31], s18 offen lds
	v_cvt_pk_bf16_f32 v105, v106, v107
	v_add_f32_e32 v220, v220, v119
	s_mov_b32 m0, s93
	v_mfma_f32_32x32x16_bf16 v[32:47], v[148:151], v[96:99], v[32:47]
	buffer_load_dwordx4 v205, s[28:31], s98 offen lds
	v_cvt_pk_bf16_f32 v106, v108, v109
	v_cvt_pk_bf16_f32 v107, v110, v111
	s_mov_b32 m0, s94
	v_mfma_f32_32x32x16_bf16 v[16:31], v[152:155], v[96:99], v[16:31]
	buffer_load_dwordx4 v206, s[36:39], s19 offen lds
	v_add_f32_e32 v220, v220, v124
	v_add_f32_e32 v220, v220, v125
	s_mov_b32 m0, s95
	v_mfma_f32_32x32x16_bf16 v[0:15], v[156:159], v[96:99], v[0:15]
	buffer_load_dwordx4 v206, s[36:39], s99 offen lds
	v_add_f32_e32 v220, v220, v126
	v_add_f32_e32 v220, v220, v127
	s_waitcnt vmcnt(4) lgkmcnt(0)
	s_barrier
	ds_read_b128 v[144:147], v240
	ds_read_b128 v[148:151], v240 offset:4096
	ds_read_b128 v[152:155], v241
	ds_read_b128 v[156:159], v241 offset:4096
	v_mfma_f32_32x32x16_bf16 v[48:63], v[224:227], v[104:107], v[48:63]
	v_add_f32_e32 v220, v220, v100
	v_add_f32_e32 v220, v220, v101
	v_add_f32_e32 v220, v220, v102
	v_mfma_f32_32x32x16_bf16 v[32:47], v[228:231], v[104:107], v[32:47]
	v_add_f32_e32 v220, v220, v103
	v_add_f32_e32 v220, v220, v108
	v_add_f32_e32 v220, v220, v109
	v_mfma_f32_32x32x16_bf16 v[16:31], v[232:235], v[104:107], v[16:31]
	v_add_f32_e32 v220, v220, v110
	v_add_f32_e32 v220, v220, v111
	v_mfma_f32_32x32x16_bf16 v[0:15], v[236:239], v[104:107], v[0:15]
	s_add_i32 s17, s14, 4
	s_min_u32 s17, s17, s15
	s_mul_i32 s18, s17, 0x30000
	s_lshl_b32 s19, s17, 7
	s_or_b32 s98, s18, 0x80
	s_add_i32 s99, s19, 0x200000
	ds_read_b128 v[224:227], v242
	ds_read_b128 v[228:231], v242 offset:4096
	ds_read_b128 v[232:235], v243
	ds_read_b128 v[236:239], v243 offset:4096
	s_waitcnt lgkmcnt(4)
	v_mfma_f32_32x32x16_bf16 v[112:127], v[144:147], v[140:143], 0
	v_exp_f32_e32 v80, v80
	v_exp_f32_e32 v81, v81
	v_add_f32_e32 v220, v220, v80
	v_add_f32_e32 v220, v220, v81
	v_mfma_f32_32x32x16_bf16 v[96:111], v[148:151], v[140:143], 0
	v_exp_f32_e32 v82, v82
	v_exp_f32_e32 v83, v83
	v_add_f32_e32 v220, v220, v82
	v_add_f32_e32 v220, v220, v83
	v_mfma_f32_32x32x16_bf16 v[112:127], v[152:155], v[136:139], v[112:127]
	v_exp_f32_e32 v84, v84
	v_exp_f32_e32 v85, v85
	v_cvt_pk_bf16_f32 v80, v80, v81
	v_add_f32_e32 v220, v220, v84
	v_mfma_f32_32x32x16_bf16 v[96:111], v[156:159], v[136:139], v[96:111]
	v_exp_f32_e32 v86, v86
	v_exp_f32_e32 v87, v87
	v_cvt_pk_bf16_f32 v81, v82, v83
	v_add_f32_e32 v220, v220, v85
	ds_read_b128 v[144:147], v244 offset:49152
	ds_read_b128 v[148:151], v244 offset:53248
	ds_read_b128 v[152:155], v244 offset:57344
	ds_read_b128 v[156:159], v244 offset:61440
	s_waitcnt lgkmcnt(4)
	v_mfma_f32_32x32x16_bf16 v[112:127], v[224:227], v[132:135], v[112:127]
	v_cvt_pk_bf16_f32 v82, v84, v85
	v_cvt_pk_bf16_f32 v83, v86, v87
	v_exp_f32_e32 v88, v88
	v_exp_f32_e32 v89, v89
	v_mfma_f32_32x32x16_bf16 v[96:111], v[228:231], v[132:135], v[96:111]
	v_exp_f32_e32 v90, v90
	v_exp_f32_e32 v91, v91
	v_add_f32_e32 v220, v220, v88
	v_add_f32_e32 v220, v220, v89
	v_mfma_f32_32x32x16_bf16 v[112:127], v[232:235], v[128:131], v[112:127]
	v_exp_f32_e32 v92, v92
	v_exp_f32_e32 v93, v93
	v_add_f32_e32 v220, v220, v90
	v_add_f32_e32 v220, v220, v91
	v_mfma_f32_32x32x16_bf16 v[96:111], v[236:239], v[128:131], v[96:111]
	v_exp_f32_e32 v94, v94
	v_exp_f32_e32 v95, v95
	v_cvt_pk_bf16_f32 v88, v88, v89
	v_add_f32_e32 v220, v220, v86
	ds_read_b128 v[224:227], v245 offset:49152
	ds_read_b128 v[228:231], v245 offset:53248
	ds_read_b128 v[232:235], v245 offset:57344
	ds_read_b128 v[236:239], v245 offset:61440
	s_waitcnt lgkmcnt(4)
	v_mfma_f32_32x32x16_bf16 v[48:63], v[144:147], v[80:83], v[48:63]
	v_cvt_pk_bf16_f32 v89, v90, v91
	v_exp_f32_e32 v64, v64
	v_cvt_pk_bf16_f32 v90, v92, v93
	v_exp_f32_e32 v65, v65
	v_mfma_f32_32x32x16_bf16 v[32:47], v[148:151], v[80:83], v[32:47]
	v_cvt_pk_bf16_f32 v91, v94, v95
	v_exp_f32_e32 v66, v66
	v_exp_f32_e32 v67, v67
	v_add_f32_e32 v220, v220, v64
	v_mfma_f32_32x32x16_bf16 v[16:31], v[152:155], v[80:83], v[16:31]
	v_exp_f32_e32 v68, v68
	v_exp_f32_e32 v69, v69
	v_add_f32_e32 v220, v220, v65
	v_add_f32_e32 v220, v220, v66
	v_mfma_f32_32x32x16_bf16 v[0:15], v[156:159], v[80:83], v[0:15]
	v_exp_f32_e32 v70, v70
	v_exp_f32_e32 v71, v71
	v_add_f32_e32 v220, v220, v67
	v_cvt_pk_bf16_f32 v64, v64, v65
	ds_read_b128 v[144:147], v246 offset:49152
	ds_read_b128 v[148:151], v246 offset:53248
	ds_read_b128 v[152:155], v246 offset:57344
	ds_read_b128 v[156:159], v246 offset:61440
	s_waitcnt lgkmcnt(4)
	v_mfma_f32_32x32x16_bf16 v[48:63], v[224:227], v[88:91], v[48:63]
	v_cvt_pk_bf16_f32 v65, v66, v67
	v_exp_f32_e32 v72, v72
	v_cvt_pk_bf16_f32 v66, v68, v69
	v_exp_f32_e32 v73, v73
	v_mfma_f32_32x32x16_bf16 v[32:47], v[228:231], v[88:91], v[32:47]
	v_cvt_pk_bf16_f32 v67, v70, v71
	v_exp_f32_e32 v74, v74
	v_exp_f32_e32 v75, v75
	v_add_f32_e32 v220, v220, v72
	v_mfma_f32_32x32x16_bf16 v[16:31], v[232:235], v[88:91], v[16:31]
	v_exp_f32_e32 v76, v76
	v_exp_f32_e32 v77, v77
	v_add_f32_e32 v220, v220, v73
	v_add_f32_e32 v220, v220, v74
	v_mfma_f32_32x32x16_bf16 v[0:15], v[236:239], v[88:91], v[0:15]
	v_exp_f32_e32 v78, v78
	v_exp_f32_e32 v79, v79
	v_add_f32_e32 v220, v220, v75
	v_cvt_pk_bf16_f32 v72, v72, v73
	ds_read_b128 v[224:227], v247 offset:49152
	ds_read_b128 v[228:231], v247 offset:53248
	ds_read_b128 v[232:235], v247 offset:57344
	ds_read_b128 v[236:239], v247 offset:61440
	s_waitcnt lgkmcnt(4)
	s_mov_b32 m0, s72
	v_mfma_f32_32x32x16_bf16 v[48:63], v[144:147], v[64:67], v[48:63]
	buffer_load_dwordx4 v205, s[28:31], s18 offen lds
	v_cvt_pk_bf16_f32 v73, v74, v75
	v_add_f32_e32 v220, v220, v87
	s_mov_b32 m0, s73
	v_mfma_f32_32x32x16_bf16 v[32:47], v[148:151], v[64:67], v[32:47]
	buffer_load_dwordx4 v205, s[28:31], s98 offen lds
	v_cvt_pk_bf16_f32 v74, v76, v77
	v_cvt_pk_bf16_f32 v75, v78, v79
	s_mov_b32 m0, s6
	v_mfma_f32_32x32x16_bf16 v[16:31], v[152:155], v[64:67], v[16:31]
	buffer_load_dwordx4 v206, s[36:39], s19 offen lds
	v_add_f32_e32 v220, v220, v92
	v_add_f32_e32 v220, v220, v93
	s_mov_b32 m0, s7
	v_mfma_f32_32x32x16_bf16 v[0:15], v[156:159], v[64:67], v[0:15]
	buffer_load_dwordx4 v206, s[36:39], s99 offen lds
	v_add_f32_e32 v220, v220, v94
	v_add_f32_e32 v220, v220, v95
	s_waitcnt vmcnt(4) lgkmcnt(0)
	s_barrier
	ds_read_b128 v[144:147], v240 offset:32768
	ds_read_b128 v[148:151], v240 offset:36864
	ds_read_b128 v[152:155], v241 offset:32768
	ds_read_b128 v[156:159], v241 offset:36864
	v_mfma_f32_32x32x16_bf16 v[48:63], v[224:227], v[72:75], v[48:63]
	v_add_f32_e32 v220, v220, v68
	v_add_f32_e32 v220, v220, v69
	v_add_f32_e32 v220, v220, v70
	v_mfma_f32_32x32x16_bf16 v[32:47], v[228:231], v[72:75], v[32:47]
	v_add_f32_e32 v220, v220, v71
	v_add_f32_e32 v220, v220, v76
	v_add_f32_e32 v220, v220, v77
	v_mfma_f32_32x32x16_bf16 v[16:31], v[232:235], v[72:75], v[16:31]
	v_add_f32_e32 v220, v220, v78
	v_add_f32_e32 v220, v220, v79
	v_mfma_f32_32x32x16_bf16 v[0:15], v[236:239], v[72:75], v[0:15]
	s_add_i32 s14, s14, 2
